# phase_cmp2 rewritten by hand: 20 bias/partial-sum loads in flight, w2 dot product 32 rows per batch double-buffered
# speedup vs baseline: 1.0214x; 1.0214x over previous
.La2_fin_win:
	ds_swizzle_b32 v189, v130 offset:0x401f
	v_lshlrev_b32_e32 v190, 16, v182
	v_mul_f32_e32 v190, 0xbfb8aa3b, v190
	v_exp_f32_e32 v190, v190
	s_waitcnt lgkmcnt(0)
	v_add_f32_e32 v188, v130, v189
	v_add_f32_e32 v190, 1.0, v190
	ds_bpermute_b32 v189, v214, v188
	v_rcp_f32_e32 v190, v190
	s_waitcnt lgkmcnt(0)
	v_add_f32_e32 v188, v188, v189
	v_max_f32_e32 v188, 0xda24260, v188
	v_div_scale_f32 v206, s[44:45], v188, v188, v190
	v_rcp_f32_e32 v207, v206
	s_nop 0
	v_fma_f32 v208, -v206, v207, 1.0
	v_fmac_f32_e32 v207, v208, v207
	v_div_scale_f32 v208, vcc, v190, v188, v190
	v_mul_f32_e32 v209, v208, v207
	v_fma_f32 v189, -v206, v209, v208
	v_fmac_f32_e32 v209, v189, v207
	v_fma_f32 v206, -v206, v209, v208
	v_div_fmas_f32 v206, v206, v207, v209
	v_div_fixup_f32 v191, v206, v188, v190
	v_lshlrev_b32_e32 v210, 16, v147
	v_and_b32_e32 v211, 0xffff0000, v147
	v_fmac_f32_e32 v210, v2, v191
	v_fmac_f32_e32 v211, v3, v191
	v_cvt_pk_bf16_f32 v147, v210, v211
	v_lshlrev_b32_e32 v210, 16, v146
	v_and_b32_e32 v211, 0xffff0000, v146
	v_fmac_f32_e32 v210, v4, v191
	v_fmac_f32_e32 v211, v5, v191
	v_cvt_pk_bf16_f32 v146, v210, v211
	v_lshlrev_b32_e32 v210, 16, v145
	v_and_b32_e32 v211, 0xffff0000, v145
	v_fmac_f32_e32 v210, v10, v191
	v_fmac_f32_e32 v211, v11, v191
	v_cvt_pk_bf16_f32 v145, v210, v211
	v_lshlrev_b32_e32 v210, 16, v144
	v_and_b32_e32 v211, 0xffff0000, v144
	v_fmac_f32_e32 v210, v12, v191
	v_fmac_f32_e32 v211, v13, v191
	v_cvt_pk_bf16_f32 v144, v210, v211
	v_lshlrev_b32_e32 v210, 16, v143
	v_and_b32_e32 v211, 0xffff0000, v143
	v_fmac_f32_e32 v210, v18, v191
	v_fmac_f32_e32 v211, v19, v191
	v_cvt_pk_bf16_f32 v143, v210, v211
	v_lshlrev_b32_e32 v210, 16, v142
	v_and_b32_e32 v211, 0xffff0000, v142
	v_fmac_f32_e32 v210, v20, v191
	v_fmac_f32_e32 v211, v21, v191
	v_cvt_pk_bf16_f32 v142, v210, v211
	v_lshlrev_b32_e32 v210, 16, v141
	v_and_b32_e32 v211, 0xffff0000, v141
	v_fmac_f32_e32 v210, v26, v191
	v_fmac_f32_e32 v211, v27, v191
	v_cvt_pk_bf16_f32 v141, v210, v211
	v_lshlrev_b32_e32 v210, 16, v140
	v_and_b32_e32 v211, 0xffff0000, v140
	v_fmac_f32_e32 v210, v28, v191
	v_fmac_f32_e32 v211, v29, v191
	v_cvt_pk_bf16_f32 v140, v210, v211
	ds_swizzle_b32 v189, v131 offset:0x401f
	v_lshlrev_b32_e32 v190, 16, v183
	v_mul_f32_e32 v190, 0xbfb8aa3b, v190
	v_exp_f32_e32 v190, v190
	s_waitcnt lgkmcnt(0)
	v_add_f32_e32 v188, v131, v189
	v_add_f32_e32 v190, 1.0, v190
	ds_bpermute_b32 v189, v214, v188
	v_rcp_f32_e32 v190, v190
	s_waitcnt lgkmcnt(0)
	v_add_f32_e32 v188, v188, v189
	v_max_f32_e32 v188, 0xda24260, v188
	v_div_scale_f32 v206, s[44:45], v188, v188, v190
	v_rcp_f32_e32 v207, v206
	s_nop 0
	v_fma_f32 v208, -v206, v207, 1.0
	v_fmac_f32_e32 v207, v208, v207
	v_div_scale_f32 v208, vcc, v190, v188, v190
	v_mul_f32_e32 v209, v208, v207
	v_fma_f32 v189, -v206, v209, v208
	v_fmac_f32_e32 v209, v189, v207
	v_fma_f32 v206, -v206, v209, v208
	v_div_fmas_f32 v206, v206, v207, v209
	v_div_fixup_f32 v191, v206, v188, v190
	v_lshlrev_b32_e32 v210, 16, v139
	v_and_b32_e32 v211, 0xffff0000, v139
	v_fmac_f32_e32 v210, v6, v191
	v_fmac_f32_e32 v211, v7, v191
	v_cvt_pk_bf16_f32 v139, v210, v211
	v_lshlrev_b32_e32 v210, 16, v138
	v_and_b32_e32 v211, 0xffff0000, v138
	v_fmac_f32_e32 v210, v8, v191
	v_fmac_f32_e32 v211, v9, v191
	v_cvt_pk_bf16_f32 v138, v210, v211
	v_lshlrev_b32_e32 v210, 16, v137
	v_and_b32_e32 v211, 0xffff0000, v137
	v_fmac_f32_e32 v210, v14, v191
	v_fmac_f32_e32 v211, v15, v191
	v_cvt_pk_bf16_f32 v137, v210, v211
	v_lshlrev_b32_e32 v210, 16, v136
	v_and_b32_e32 v211, 0xffff0000, v136
	v_fmac_f32_e32 v210, v16, v191
	v_fmac_f32_e32 v211, v17, v191
	v_cvt_pk_bf16_f32 v136, v210, v211
	v_lshlrev_b32_e32 v210, 16, v123
	v_and_b32_e32 v211, 0xffff0000, v123
	v_fmac_f32_e32 v210, v22, v191
	v_fmac_f32_e32 v211, v23, v191
	v_cvt_pk_bf16_f32 v123, v210, v211
	v_lshlrev_b32_e32 v210, 16, v122
	v_and_b32_e32 v211, 0xffff0000, v122
	v_fmac_f32_e32 v210, v24, v191
	v_fmac_f32_e32 v211, v25, v191
	v_cvt_pk_bf16_f32 v122, v210, v211
	v_lshlrev_b32_e32 v210, 16, v121
	v_and_b32_e32 v211, 0xffff0000, v121
	v_fmac_f32_e32 v210, v30, v191
	v_fmac_f32_e32 v211, v31, v191
	v_cvt_pk_bf16_f32 v121, v210, v211
	v_lshlrev_b32_e32 v210, 16, v120
	v_and_b32_e32 v211, 0xffff0000, v120
	v_fmac_f32_e32 v210, v32, v191
	v_fmac_f32_e32 v211, v33, v191
	v_cvt_pk_bf16_f32 v120, v210, v211
	v_mov_b32_e32 v188, v147
	v_mov_b32_e32 v189, v146
	global_store_dwordx2 v184, v[188:189], s[38:39]
	s_nop 1
	v_mov_b32_e32 v188, v145
	v_mov_b32_e32 v189, v144
	global_store_dwordx2 v184, v[188:189], s[38:39] offset:32
	s_nop 1
	v_mov_b32_e32 v188, v143
	v_mov_b32_e32 v189, v142
	global_store_dwordx2 v184, v[188:189], s[38:39] offset:64
	s_nop 1
	v_mov_b32_e32 v188, v141
	v_mov_b32_e32 v189, v140
	global_store_dwordx2 v184, v[188:189], s[38:39] offset:96
	s_nop 1
	v_mov_b32_e32 v188, v139
	v_mov_b32_e32 v189, v138
	global_store_dwordx2 v185, v[188:189], s[38:39]
	s_nop 1
	v_mov_b32_e32 v188, v137
	v_mov_b32_e32 v189, v136
	global_store_dwordx2 v185, v[188:189], s[38:39] offset:32
	s_nop 1
	v_mov_b32_e32 v188, v123
	v_mov_b32_e32 v189, v122
	global_store_dwordx2 v185, v[188:189], s[38:39] offset:64
	s_nop 1
	v_mov_b32_e32 v188, v121
	v_mov_b32_e32 v189, v120
	global_store_dwordx2 v185, v[188:189], s[38:39] offset:96
	s_nop 1
	v_readlane_b32 s76, v236, 29
	v_readlane_b32 s77, v236, 30
	v_readlane_b32 s78, v236, 31
	v_readlane_b32 s79, v236, 32
	v_readlane_b32 s80, v236, 33
	v_readlane_b32 s81, v236, 34
	v_readlane_b32 s82, v236, 35
	v_readlane_b32 s83, v236, 36
	v_readlane_b32 s84, v236, 37
	v_readlane_b32 s85, v236, 38
	v_readlane_b32 s86, v236, 39
	v_readlane_b32 s87, v236, 40
	v_readlane_b32 s88, v236, 41
	v_readlane_b32 s89, v236, 42
	v_readlane_b32 s90, v236, 43
	v_readlane_b32 s91, v236, 44
	v_readlane_b32 s44, v236, 13
	v_readlane_b32 s45, v236, 14
	v_readlane_b32 s46, v236, 15
	v_readlane_b32 s47, v236, 16
	v_readlane_b32 s48, v236, 17
	v_readlane_b32 s49, v236, 18
	v_readlane_b32 s50, v236, 19
	v_readlane_b32 s51, v236, 20
	v_readlane_b32 s52, v236, 21
	v_readlane_b32 s53, v236, 22
	v_readlane_b32 s54, v236, 23
	v_readlane_b32 s55, v236, 24
	v_readlane_b32 s56, v236, 25
	v_readlane_b32 s57, v236, 26
	v_readlane_b32 s58, v236, 27
	v_readlane_b32 s59, v236, 28
	v_readlane_b32 s34, v236, 45
	v_readlane_b32 s35, v236, 46
	s_movk_i32 s33, 0x70
	s_movk_i32 s36, 0x3ff
	s_movk_i32 s38, 0x1680
	s_movk_i32 s43, 0x880
	s_movk_i32 s92, 0x480
	s_movk_i32 s93, 0x3300
	s_movk_i32 s94, 0x2080
	s_movk_i32 s95, 0x3000
	s_mov_b32 s37, 0x5a000
	s_mov_b32 s39, 0x2d000
	s_mov_b32 s42, 0x87000
	s_mov_b64 s[0:1], 0
	s_branch .LBB0_143
.Ltramp564:
	s_branch .LBB0_564
.Ltramp36:
	s_branch .LBB0_36
.Ltramp37:
	s_branch .LBB0_37
.Ltramp38:
	s_branch .LBB0_38
.LBB0_192:
	s_mov_b64 s[0:1], -1
	s_cbranch_execnz .LBB0_530

.LBB0_199:
	v_ashrrev_i32_e32 v10, 10, v3
	v_lshlrev_b32_e32 v24, 8, v10
	v_or_b32_e32 v14, v24, v2
	v_readlane_b32 s10, v237, 63
	v_readlane_b32 s11, v236, 0
	v_ashrrev_i32_e32 v15, 31, v14
	v_lshlrev_b32_e32 v0, 10, v3
	v_ashrrev_i32_e32 v11, 31, v10
	v_lshl_add_u64 v[22:23], v[14:15], 2, s[10:11]
	v_and_b32_e32 v0, 0xffc00, v0
	v_lshlrev_b64 v[12:13], 20, v[10:11]
	v_lshl_add_u64 v[14:15], v[6:7], 0, v[0:1]
	v_lshl_add_u64 v[18:19], v[14:15], 0, v[12:13]
	s_mov_b64 s[4:5], 0x200000
	v_lshl_add_u64 v[26:27], v[18:19], 0, s[4:5]
	s_mov_b64 s[4:5], 0x400000
	v_lshl_add_u64 v[28:29], v[18:19], 0, s[4:5]
	s_mov_b64 s[4:5], 0x600000
	v_lshl_add_u64 v[30:31], v[18:19], 0, s[4:5]
	global_load_dword v32, v[22:23], off
	global_load_dword v36, v[18:19], off
	global_load_dword v40, v[26:27], off
	global_load_dword v44, v[28:29], off
	global_load_dword v48, v[30:31], off
	global_load_dword v33, v[22:23], off offset:256
	global_load_dword v37, v[18:19], off offset:256
	global_load_dword v41, v[26:27], off offset:256
	global_load_dword v45, v[28:29], off offset:256
	global_load_dword v49, v[30:31], off offset:256
	global_load_dword v34, v[22:23], off offset:512
	global_load_dword v38, v[18:19], off offset:512
	global_load_dword v42, v[26:27], off offset:512
	global_load_dword v46, v[28:29], off offset:512
	global_load_dword v50, v[30:31], off offset:512
	global_load_dword v35, v[22:23], off offset:768
	global_load_dword v39, v[18:19], off offset:768
	global_load_dword v43, v[26:27], off offset:768
	global_load_dword v47, v[28:29], off offset:768
	global_load_dword v51, v[30:31], off offset:768
	v_readlane_b32 s4, v236, 11
	v_add_u32_e32 v10, s4, v10
	v_ashrrev_i32_e32 v11, 31, v10
	v_lshlrev_b64 v[10:11], 16, v[10:11]
	v_lshl_add_u64 v[10:11], v[8:9], 0, v[10:11]
	s_waitcnt vmcnt(15)
	v_add_f32_e32 v52, v32, v36
	v_add_f32_e32 v52, v52, v40
	v_add_f32_e32 v52, v52, v44
	v_add_f32_e32 v52, v52, v48
	s_waitcnt vmcnt(10)
	v_add_f32_e32 v53, v33, v37
	v_add_f32_e32 v53, v53, v41
	v_add_f32_e32 v53, v53, v45
	v_add_f32_e32 v53, v53, v49
	s_waitcnt vmcnt(5)
	v_add_f32_e32 v54, v34, v38
	v_add_f32_e32 v54, v54, v42
	v_add_f32_e32 v54, v54, v46
	v_add_f32_e32 v54, v54, v50
	s_waitcnt vmcnt(0)
	v_add_f32_e32 v55, v35, v39
	v_add_f32_e32 v55, v55, v43
	v_add_f32_e32 v55, v55, v47
	v_add_f32_e32 v55, v55, v51
	v_mul_f32_e32 v56, 0x3d372713, v52
	v_mul_f32_e32 v57, 0x3d372713, v53
	v_mul_f32_e32 v58, 0x3d372713, v54
	v_mul_f32_e32 v59, 0x3d372713, v55
	v_mul_f32_e32 v56, v52, v56
	v_mul_f32_e32 v57, v53, v57
	v_mul_f32_e32 v58, v54, v58
	v_mul_f32_e32 v59, v55, v59
	v_fma_f32 v56, v52, v56, v52
	v_fma_f32 v57, v53, v57, v53
	v_fma_f32 v58, v54, v58, v54
	v_fma_f32 v59, v55, v59, v55
	v_mul_f32_e32 v56, 0x3fcc422a, v56
	v_mul_f32_e32 v57, 0x3fcc422a, v57
	v_mul_f32_e32 v58, 0x3fcc422a, v58
	v_mul_f32_e32 v59, 0x3fcc422a, v59
	v_mul_f32_e32 v56, 0xbfb8aa3b, v56
	v_mul_f32_e32 v57, 0xbfb8aa3b, v57
	v_mul_f32_e32 v58, 0xbfb8aa3b, v58
	v_mul_f32_e32 v59, 0xbfb8aa3b, v59
	v_exp_f32_e32 v56, v56
	v_exp_f32_e32 v57, v57
	v_exp_f32_e32 v58, v58
	v_exp_f32_e32 v59, v59
	v_add_f32_e32 v56, 1.0, v56
	v_add_f32_e32 v57, 1.0, v57
	v_add_f32_e32 v58, 1.0, v58
	v_add_f32_e32 v59, 1.0, v59
	v_rcp_f32_e32 v56, v56
	v_rcp_f32_e32 v57, v57
	v_rcp_f32_e32 v58, v58
	v_rcp_f32_e32 v59, v59
	v_mul_f32_e32 v52, v52, v56
	v_mul_f32_e32 v53, v53, v57
	v_mul_f32_e32 v54, v54, v58
	v_mul_f32_e32 v55, v55, v59
	ds_write2st64_b32 v17, v52, v53 offset1:1
	ds_write2st64_b32 v17, v54, v55 offset0:2 offset1:3
	v_mov_b32_e32 v15, 0
	v_mov_b32_e32 v0, v16
	s_mov_b64 s[4:5], 0
	v_mov_b64_e32 v[12:13], v[10:11]
	global_load_dword v32, v[12:13], off
	global_load_dword v33, v[12:13], off offset:256
	global_load_dword v34, v[12:13], off offset:512
	global_load_dword v35, v[12:13], off offset:768
	global_load_dword v36, v[12:13], off offset:1024
	global_load_dword v37, v[12:13], off offset:1280
	global_load_dword v38, v[12:13], off offset:1536
	global_load_dword v39, v[12:13], off offset:1792
	global_load_dword v40, v[12:13], off offset:2048
	global_load_dword v41, v[12:13], off offset:2304
	global_load_dword v42, v[12:13], off offset:2560
	global_load_dword v43, v[12:13], off offset:2816
	global_load_dword v44, v[12:13], off offset:3072
	global_load_dword v45, v[12:13], off offset:3328
	global_load_dword v46, v[12:13], off offset:3584
	global_load_dword v47, v[12:13], off offset:3840
	v_add_co_u32_e32 v12, vcc, 0x1000, v12
	s_nop 1
	v_addc_co_u32_e32 v13, vcc, 0, v13, vcc
	global_load_dword v48, v[12:13], off
	global_load_dword v49, v[12:13], off offset:256
	global_load_dword v50, v[12:13], off offset:512
	global_load_dword v51, v[12:13], off offset:768
	global_load_dword v52, v[12:13], off offset:1024
	global_load_dword v53, v[12:13], off offset:1280
	global_load_dword v54, v[12:13], off offset:1536
	global_load_dword v55, v[12:13], off offset:1792
	global_load_dword v56, v[12:13], off offset:2048
	global_load_dword v57, v[12:13], off offset:2304
	global_load_dword v58, v[12:13], off offset:2560
	global_load_dword v59, v[12:13], off offset:2816
	global_load_dword v60, v[12:13], off offset:3072
	global_load_dword v61, v[12:13], off offset:3328
	global_load_dword v62, v[12:13], off offset:3584
	global_load_dword v63, v[12:13], off offset:3840
	v_add_co_u32_e32 v12, vcc, 0x1000, v12
	s_nop 1
	v_addc_co_u32_e32 v13, vcc, 0, v13, vcc
	ds_read_b128 v[96:99], v0
	ds_read_b128 v[100:103], v0 offset:16
	ds_read_b128 v[104:107], v0 offset:32
	ds_read_b128 v[108:111], v0 offset:48
	ds_read_b128 v[112:115], v0 offset:64
	ds_read_b128 v[116:119], v0 offset:80
	ds_read_b128 v[120:123], v0 offset:96
	ds_read_b128 v[124:127], v0 offset:112
	s_mov_b32 s4, 0
.Lc2_loop:
	global_load_dword v64, v[12:13], off
	global_load_dword v65, v[12:13], off offset:256
	global_load_dword v66, v[12:13], off offset:512
	global_load_dword v67, v[12:13], off offset:768
	global_load_dword v68, v[12:13], off offset:1024
	global_load_dword v69, v[12:13], off offset:1280
	global_load_dword v70, v[12:13], off offset:1536
	global_load_dword v71, v[12:13], off offset:1792
	global_load_dword v72, v[12:13], off offset:2048
	global_load_dword v73, v[12:13], off offset:2304
	global_load_dword v74, v[12:13], off offset:2560
	global_load_dword v75, v[12:13], off offset:2816
	global_load_dword v76, v[12:13], off offset:3072
	global_load_dword v77, v[12:13], off offset:3328
	global_load_dword v78, v[12:13], off offset:3584
	global_load_dword v79, v[12:13], off offset:3840
	v_add_co_u32_e32 v12, vcc, 0x1000, v12
	s_nop 1
	v_addc_co_u32_e32 v13, vcc, 0, v13, vcc
	global_load_dword v80, v[12:13], off
	global_load_dword v81, v[12:13], off offset:256
	global_load_dword v82, v[12:13], off offset:512
	global_load_dword v83, v[12:13], off offset:768
	global_load_dword v84, v[12:13], off offset:1024
	global_load_dword v85, v[12:13], off offset:1280
	global_load_dword v86, v[12:13], off offset:1536
	global_load_dword v87, v[12:13], off offset:1792
	global_load_dword v88, v[12:13], off offset:2048
	global_load_dword v89, v[12:13], off offset:2304
	global_load_dword v90, v[12:13], off offset:2560
	global_load_dword v91, v[12:13], off offset:2816
	global_load_dword v92, v[12:13], off offset:3072
	global_load_dword v93, v[12:13], off offset:3328
	global_load_dword v94, v[12:13], off offset:3584
	global_load_dword v95, v[12:13], off offset:3840
	v_add_co_u32_e32 v12, vcc, 0x1000, v12
	s_nop 1
	v_addc_co_u32_e32 v13, vcc, 0, v13, vcc
	ds_read_b128 v[128:131], v0 offset:128
	ds_read_b128 v[132:135], v0 offset:144
	ds_read_b128 v[136:139], v0 offset:160
	ds_read_b128 v[140:143], v0 offset:176
	ds_read_b128 v[144:147], v0 offset:192
	ds_read_b128 v[148:151], v0 offset:208
	ds_read_b128 v[152:155], v0 offset:224
	ds_read_b128 v[156:159], v0 offset:240
	s_waitcnt vmcnt(32) lgkmcnt(8)
	v_fmac_f32_e32 v15, v96, v32
	v_fmac_f32_e32 v15, v97, v33
	v_fmac_f32_e32 v15, v98, v34
	v_fmac_f32_e32 v15, v99, v35
	v_fmac_f32_e32 v15, v100, v36
	v_fmac_f32_e32 v15, v101, v37
	v_fmac_f32_e32 v15, v102, v38
	v_fmac_f32_e32 v15, v103, v39
	v_fmac_f32_e32 v15, v104, v40
	v_fmac_f32_e32 v15, v105, v41
	v_fmac_f32_e32 v15, v106, v42
	v_fmac_f32_e32 v15, v107, v43
	v_fmac_f32_e32 v15, v108, v44
	v_fmac_f32_e32 v15, v109, v45
	v_fmac_f32_e32 v15, v110, v46
	v_fmac_f32_e32 v15, v111, v47
	v_fmac_f32_e32 v15, v112, v48
	v_fmac_f32_e32 v15, v113, v49
	v_fmac_f32_e32 v15, v114, v50
	v_fmac_f32_e32 v15, v115, v51
	v_fmac_f32_e32 v15, v116, v52
	v_fmac_f32_e32 v15, v117, v53
	v_fmac_f32_e32 v15, v118, v54
	v_fmac_f32_e32 v15, v119, v55
	v_fmac_f32_e32 v15, v120, v56
	v_fmac_f32_e32 v15, v121, v57
	v_fmac_f32_e32 v15, v122, v58
	v_fmac_f32_e32 v15, v123, v59
	v_fmac_f32_e32 v15, v124, v60
	v_fmac_f32_e32 v15, v125, v61
	v_fmac_f32_e32 v15, v126, v62
	v_fmac_f32_e32 v15, v127, v63
	s_cmp_eq_u32 s4, 3
	s_cbranch_scc1 .Lc2_last
	global_load_dword v32, v[12:13], off
	global_load_dword v33, v[12:13], off offset:256
	global_load_dword v34, v[12:13], off offset:512
	global_load_dword v35, v[12:13], off offset:768
	global_load_dword v36, v[12:13], off offset:1024
	global_load_dword v37, v[12:13], off offset:1280
	global_load_dword v38, v[12:13], off offset:1536
	global_load_dword v39, v[12:13], off offset:1792
	global_load_dword v40, v[12:13], off offset:2048
	global_load_dword v41, v[12:13], off offset:2304
	global_load_dword v42, v[12:13], off offset:2560
	global_load_dword v43, v[12:13], off offset:2816
	global_load_dword v44, v[12:13], off offset:3072
	global_load_dword v45, v[12:13], off offset:3328
	global_load_dword v46, v[12:13], off offset:3584
	global_load_dword v47, v[12:13], off offset:3840
	v_add_co_u32_e32 v12, vcc, 0x1000, v12
	s_nop 1
	v_addc_co_u32_e32 v13, vcc, 0, v13, vcc
	global_load_dword v48, v[12:13], off
	global_load_dword v49, v[12:13], off offset:256
	global_load_dword v50, v[12:13], off offset:512
	global_load_dword v51, v[12:13], off offset:768
	global_load_dword v52, v[12:13], off offset:1024
	global_load_dword v53, v[12:13], off offset:1280
	global_load_dword v54, v[12:13], off offset:1536
	global_load_dword v55, v[12:13], off offset:1792
	global_load_dword v56, v[12:13], off offset:2048
	global_load_dword v57, v[12:13], off offset:2304
	global_load_dword v58, v[12:13], off offset:2560
	global_load_dword v59, v[12:13], off offset:2816
	global_load_dword v60, v[12:13], off offset:3072
	global_load_dword v61, v[12:13], off offset:3328
	global_load_dword v62, v[12:13], off offset:3584
	global_load_dword v63, v[12:13], off offset:3840
	v_add_co_u32_e32 v12, vcc, 0x1000, v12
	s_nop 1
	v_addc_co_u32_e32 v13, vcc, 0, v13, vcc
	ds_read_b128 v[96:99], v0 offset:256
	ds_read_b128 v[100:103], v0 offset:272
	ds_read_b128 v[104:107], v0 offset:288
	ds_read_b128 v[108:111], v0 offset:304
	ds_read_b128 v[112:115], v0 offset:320
	ds_read_b128 v[116:119], v0 offset:336
	ds_read_b128 v[120:123], v0 offset:352
	ds_read_b128 v[124:127], v0 offset:368
	v_add_u32_e32 v0, 0x100, v0
	s_waitcnt vmcnt(32) lgkmcnt(8)
	v_fmac_f32_e32 v15, v128, v64
	v_fmac_f32_e32 v15, v129, v65
	v_fmac_f32_e32 v15, v130, v66
	v_fmac_f32_e32 v15, v131, v67
	v_fmac_f32_e32 v15, v132, v68
	v_fmac_f32_e32 v15, v133, v69
	v_fmac_f32_e32 v15, v134, v70
	v_fmac_f32_e32 v15, v135, v71
	v_fmac_f32_e32 v15, v136, v72
	v_fmac_f32_e32 v15, v137, v73
	v_fmac_f32_e32 v15, v138, v74
	v_fmac_f32_e32 v15, v139, v75
	v_fmac_f32_e32 v15, v140, v76
	v_fmac_f32_e32 v15, v141, v77
	v_fmac_f32_e32 v15, v142, v78
	v_fmac_f32_e32 v15, v143, v79
	v_fmac_f32_e32 v15, v144, v80
	v_fmac_f32_e32 v15, v145, v81
	v_fmac_f32_e32 v15, v146, v82
	v_fmac_f32_e32 v15, v147, v83
	v_fmac_f32_e32 v15, v148, v84
	v_fmac_f32_e32 v15, v149, v85
	v_fmac_f32_e32 v15, v150, v86
	v_fmac_f32_e32 v15, v151, v87
	v_fmac_f32_e32 v15, v152, v88
	v_fmac_f32_e32 v15, v153, v89
	v_fmac_f32_e32 v15, v154, v90
	v_fmac_f32_e32 v15, v155, v91
	v_fmac_f32_e32 v15, v156, v92
	v_fmac_f32_e32 v15, v157, v93
	v_fmac_f32_e32 v15, v158, v94
	v_fmac_f32_e32 v15, v159, v95
	s_add_i32 s4, s4, 1
	s_branch .Lc2_loop
.Lc2_last:
	s_waitcnt vmcnt(0) lgkmcnt(0)
	v_fmac_f32_e32 v15, v128, v64
	v_fmac_f32_e32 v15, v129, v65
	v_fmac_f32_e32 v15, v130, v66
	v_fmac_f32_e32 v15, v131, v67
	v_fmac_f32_e32 v15, v132, v68
	v_fmac_f32_e32 v15, v133, v69
	v_fmac_f32_e32 v15, v134, v70
	v_fmac_f32_e32 v15, v135, v71
	v_fmac_f32_e32 v15, v136, v72
	v_fmac_f32_e32 v15, v137, v73
	v_fmac_f32_e32 v15, v138, v74
	v_fmac_f32_e32 v15, v139, v75
	v_fmac_f32_e32 v15, v140, v76
	v_fmac_f32_e32 v15, v141, v77
	v_fmac_f32_e32 v15, v142, v78
	v_fmac_f32_e32 v15, v143, v79
	v_fmac_f32_e32 v15, v144, v80
	v_fmac_f32_e32 v15, v145, v81
	v_fmac_f32_e32 v15, v146, v82
	v_fmac_f32_e32 v15, v147, v83
	v_fmac_f32_e32 v15, v148, v84
	v_fmac_f32_e32 v15, v149, v85
	v_fmac_f32_e32 v15, v150, v86
	v_fmac_f32_e32 v15, v151, v87
	v_fmac_f32_e32 v15, v152, v88
	v_fmac_f32_e32 v15, v153, v89
	v_fmac_f32_e32 v15, v154, v90
	v_fmac_f32_e32 v15, v155, v91
	v_fmac_f32_e32 v15, v156, v92
	v_fmac_f32_e32 v15, v157, v93
	v_fmac_f32_e32 v15, v158, v94
	v_fmac_f32_e32 v15, v159, v95
	v_readlane_b32 s4, v237, 57
	v_readlane_b32 s5, v237, 58
	v_and_b32_e32 v13, 1, v3
	v_bfe_u32 v12, v3, 1, 7
	v_cmp_lt_u32_e32 vcc, s36, v3
	v_mov_b64_e32 v[10:11], s[4:5]
	v_readlane_b32 s6, v237, 59
	v_readlane_b32 s7, v237, 60
	v_readlane_b32 s8, v237, 61
	v_readlane_b32 s9, v237, 62
	v_readlane_b32 s10, v237, 63
	v_readlane_b32 s11, v236, 0
	s_and_saveexec_b64 s[4:5], vcc
	s_xor_b64 s[4:5], exec, s[4:5]
	s_cbranch_execz .LBB0_203
	v_lshrrev_b32_e32 v0, 1, v3
	v_and_b32_e32 v0, 0x180, v0
	v_lshlrev_b32_e32 v10, 6, v13
	v_readlane_b32 s8, v237, 57
	v_or3_b32 v0, v0, v10, v2
	v_readlane_b32 s10, v237, 59
	v_readlane_b32 s11, v237, 60
	v_cvt_pk_bf16_f32 v14, v15, v1
	v_lshl_or_b32 v0, v0, 7, v12
	v_readlane_b32 s9, v237, 58
	v_readlane_b32 s12, v237, 61
	v_readlane_b32 s13, v237, 62
	v_readlane_b32 s14, v237, 63
	v_readlane_b32 s15, v236, 0
	v_mov_b64_e32 v[10:11], s[10:11]
